# XCC-local barriers as flat arrive-and-poll counters (one non-returning atomic + sc1 poll + L1 invalidate)
# speedup vs baseline: 1.0154x; 1.0041x over previous
_Z6mk_fwd4Args:
	s_load_dword s33, s[0:1], 0xa0
	s_mov_b64 s[92:93], s[0:1]
	v_and_b32_e32 v1, 0x3ff, v0
	s_add_u32 s8, s92, 0xa0
	s_getreg_b32 s0, hwreg(HW_REG_XCC_ID, 0, 4)
	v_readfirstlane_b32 s74, v1
	s_addc_u32 s9, s93, 0
	s_and_b32 s75, s0, 15
	v_cmp_eq_u32_e32 vcc, 0, v1
	s_and_saveexec_b64 s[0:1], vcc
	s_cbranch_execz .LBB0_3
	s_add_i32 s3, 0, 0x20100
	v_mov_b32_e32 v2, 0
	v_mov_b32_e32 v3, s3
	s_add_i32 s3, 0, 0x20104
	s_mov_b64 s[4:5], exec
	ds_write_b32 v3, v2
	v_mov_b32_e32 v3, 0x2010c
	ds_write_b32 v3, v2
	v_mov_b32_e32 v3, s3
	ds_write_b32 v3, v2
	v_mbcnt_lo_u32_b32 v2, s4, 0
	v_mbcnt_hi_u32_b32 v2, s5, v2
	v_cmp_eq_u32_e32 vcc, 0, v2
	s_and_b64 s[6:7], exec, vcc
	s_mov_b64 exec, s[6:7]
	s_cbranch_execz .LBB0_3
	s_load_dwordx2 s[6:7], s[92:93], 0x78
	s_lshl_b32 s3, s75, 8
	v_mov_b32_e32 v2, 0xf0000
	s_waitcnt lgkmcnt(0)
	s_add_u32 s6, s6, s3
	s_addc_u32 s7, s7, 0
	s_bcnt1_i32_b64 s3, s[4:5]
	v_mov_b32_e32 v3, s3
	global_atomic_add v3, v2, v3, s[6:7] offset:1024 sc0
	s_waitcnt vmcnt(0)
	v_lshlrev_b32_e32 v3, 3, v3
	v_or_b32_e32 v3, s75, v3
	v_mov_b32_e32 v2, 0x20108
	ds_write_b32 v2, v3

.LBB0_309:
	v_readlane_b32 s0, v252, 6
	v_readlane_b32 s1, v252, 7
	s_waitcnt vmcnt(0)
	s_andn2_b64 vcc, exec, s[0:1]
	s_waitcnt vmcnt(0)
	v_cndmask_b32_e64 v0, 0, 1, s[0:1]
	v_cmp_ne_u32_e64 s[4:5], 1, v0
	s_barrier
	s_nop 0
	v_writelane_b32 v255, s4, 6
	s_nop 1
	v_writelane_b32 v255, s5, 7
	s_cbranch_vccnz .LBB0_363
	v_mbcnt_lo_u32_b32 v0, -1, 0
	v_mbcnt_hi_u32_b32 v0, -1, v0
	s_nop 0
	v_cmp_eq_u32_e32 vcc, 0, v0
	s_and_saveexec_b64 s[4:5], vcc
	s_cbranch_execz .LBB0_362
	s_cmp_eq_u32 s33, 0x100
	s_cbranch_scc0 .Llb_skip_b1
	v_readlane_b32 s0, v253, 35
	v_readlane_b32 s1, v253, 36
	s_and_b32 s6, s2, 7
	s_lshl_b32 s6, s6, 8
	s_nop 3
	s_add_u32 s0, s0, s6
	s_addc_u32 s1, s1, 0
	s_add_u32 s0, s0, 0xf3700
	s_addc_u32 s1, s1, 0
	v_mov_b32_e32 v0, 0x2010c
	ds_read_b32 v1, v0
	v_mov_b32_e32 v2, 1
	global_atomic_add v177, v2, s[0:1]
	s_waitcnt lgkmcnt(0)
	v_add_u32_e32 v1, 1, v1
	ds_write_b32 v0, v1
	v_lshlrev_b32_e32 v1, 5, v1
	s_mov_b32 s12, 0
.Llb_spin_b1:
	global_load_dword v2, v177, s[0:1] sc1
	s_waitcnt vmcnt(0)
	v_cmp_ge_u32_e32 vcc, v2, v1
	s_cbranch_vccnz .Llb_done_b1
	s_sleep 1
	s_add_u32 s12, s12, 1
	s_cmp_lt_u32 s12, 0x10000
	s_cbranch_scc1 .Llb_spin_b1
.Llb_done_b1:
	buffer_inv sc1
	s_waitcnt vmcnt(0) lgkmcnt(0)
	s_branch .LBB0_362

.LBB0_505:
	s_waitcnt vmcnt(0)
	v_readlane_b32 s0, v255, 6
	v_readlane_b32 s1, v255, 7
	s_and_b64 vcc, exec, s[0:1]
	s_barrier
	s_cbranch_vccnz .LBB0_559
	v_mbcnt_lo_u32_b32 v0, -1, 0
	v_mbcnt_hi_u32_b32 v0, -1, v0
	s_nop 0
	v_cmp_eq_u32_e32 vcc, 0, v0
	s_and_saveexec_b64 s[4:5], vcc
	s_cbranch_execz .LBB0_558
	s_cmp_eq_u32 s33, 0x100
	s_cbranch_scc0 .Llb_skip_b2
	v_readlane_b32 s98, v255, 5
	s_nop 3
	s_cmp_eq_u32 s98, 0
	s_cbranch_scc1 .Llb_skip_b2
	v_readlane_b32 s0, v253, 35
	v_readlane_b32 s1, v253, 36
	s_and_b32 s6, s2, 7
	s_lshl_b32 s6, s6, 8
	s_nop 3
	s_add_u32 s0, s0, s6
	s_addc_u32 s1, s1, 0
	s_add_u32 s0, s0, 0xf3700
	s_addc_u32 s1, s1, 0
	v_mov_b32_e32 v0, 0x2010c
	ds_read_b32 v1, v0
	v_mov_b32_e32 v2, 1
	global_atomic_add v177, v2, s[0:1]
	s_waitcnt lgkmcnt(0)
	v_add_u32_e32 v1, 1, v1
	ds_write_b32 v0, v1
	v_lshlrev_b32_e32 v1, 5, v1
	s_mov_b32 s12, 0

.LBB0_595:
	s_waitcnt vmcnt(0)
	v_readlane_b32 s0, v255, 6
	v_readlane_b32 s1, v255, 7
	s_and_b64 vcc, exec, s[0:1]
	s_barrier
	s_cbranch_vccnz .LBB0_649
	v_mbcnt_lo_u32_b32 v0, -1, 0
	v_mbcnt_hi_u32_b32 v0, -1, v0
	s_nop 0
	v_cmp_eq_u32_e32 vcc, 0, v0
	s_and_saveexec_b64 s[4:5], vcc
	s_cbranch_execz .LBB0_648
	s_cmp_eq_u32 s33, 0x100
	s_cbranch_scc0 .Llb_skip_b3
	v_readlane_b32 s0, v253, 35
	v_readlane_b32 s1, v253, 36
	s_and_b32 s6, s2, 7
	s_lshl_b32 s6, s6, 8
	s_nop 3
	s_add_u32 s0, s0, s6
	s_addc_u32 s1, s1, 0
	s_add_u32 s0, s0, 0xf3700
	s_addc_u32 s1, s1, 0
	v_mov_b32_e32 v0, 0x2010c
	ds_read_b32 v1, v0
	v_mov_b32_e32 v2, 1
	global_atomic_add v177, v2, s[0:1]
	s_waitcnt lgkmcnt(0)
	v_add_u32_e32 v1, 1, v1
	ds_write_b32 v0, v1
	v_lshlrev_b32_e32 v1, 5, v1
	s_mov_b32 s12, 0
